# MLA GEN (diagonal) loop: K/V fragment LDS reads de-serialised (ring of free VGPR buffers, counted waits); on top of v138
# baseline (speedup 1.0000x reference)
.LBB0_1391:
	s_mul_i32 s43, s19, 0x3400
	v_add_u32_e32 v1, s43, v216
	ds_read_b128 v[186:189], v1 offset:0
	ds_read_b128 v[190:193], v1 offset:32
	ds_read_b128 v[194:197], v1 offset:6656
	ds_read_b128 v[230:233], v1 offset:6688
	ds_read_b128 v[234:237], v1 offset:64
	ds_read_b128 v[238:241], v1 offset:6720
	ds_read_b128 v[158:161], v1 offset:96
	s_waitcnt lgkmcnt(6)
	v_mfma_f32_32x32x16_bf16 v[34:49], v[186:189], v[98:101], 0
	ds_read_b128 v[186:189], v1 offset:6752
	s_waitcnt lgkmcnt(6)
	v_mfma_f32_32x32x16_bf16 v[34:49], v[190:193], v[102:105], v[34:49]
	ds_read_b128 v[190:193], v1 offset:128
	s_waitcnt lgkmcnt(6)
	v_mfma_f32_32x32x16_bf16 v[50:65], v[194:197], v[98:101], 0
	ds_read_b128 v[194:197], v1 offset:6784
	s_waitcnt lgkmcnt(6)
	v_mfma_f32_32x32x16_bf16 v[50:65], v[230:233], v[102:105], v[50:65]
	ds_read_b128 v[230:233], v1 offset:160
	s_waitcnt lgkmcnt(6)
	v_mfma_f32_32x32x16_bf16 v[34:49], v[234:237], v[106:109], v[34:49]
	ds_read_b128 v[234:237], v1 offset:6816
	s_waitcnt lgkmcnt(6)
	v_mfma_f32_32x32x16_bf16 v[50:65], v[238:241], v[106:109], v[50:65]
	s_waitcnt lgkmcnt(5)
	v_mfma_f32_32x32x16_bf16 v[34:49], v[158:161], v[110:113], v[34:49]
	s_waitcnt lgkmcnt(4)
	v_mfma_f32_32x32x16_bf16 v[50:65], v[186:189], v[110:113], v[50:65]
	s_waitcnt lgkmcnt(3)
	v_mfma_f32_32x32x16_bf16 v[34:49], v[190:193], v[114:117], v[34:49]
	s_waitcnt lgkmcnt(2)
	v_mfma_f32_32x32x16_bf16 v[50:65], v[194:197], v[114:117], v[50:65]
	s_waitcnt lgkmcnt(1)
	v_mfma_f32_32x32x16_bf16 v[34:49], v[230:233], v[118:121], v[34:49]
	s_waitcnt lgkmcnt(0)
	v_mfma_f32_32x32x16_bf16 v[50:65], v[234:237], v[118:121], v[50:65]
	s_andn2_b64 vcc, exec, s[16:17]
	s_cbranch_vccnz .LBB0_1386
.LBB0_1392:
	v_exp_f32_e32 v66, v66
	v_exp_f32_e32 v67, v67
	v_exp_f32_e32 v161, v70
	s_mul_i32 s16, s42, 0x2400
	v_add_f32_e32 v1, 0, v66
	v_cvt_pk_bf16_f32 v70, v66, v67
	v_exp_f32_e32 v66, v82
	v_exp_f32_e32 v159, v68
	v_exp_f32_e32 v69, v69
	v_exp_f32_e32 v163, v71
	v_exp_f32_e32 v165, v72
	v_exp_f32_e32 v167, v73
	v_exp_f32_e32 v179, v78
	v_exp_f32_e32 v181, v79
	v_pk_add_f32 v[78:79], v[66:67], v[0:1]
	v_add_u32_e32 v1, s16, v217
	v_exp_f32_e32 v158, v83
	v_exp_f32_e32 v68, v84
	v_exp_f32_e32 v160, v85
	v_exp_f32_e32 v162, v86
	v_exp_f32_e32 v164, v87
	v_exp_f32_e32 v166, v88
	v_exp_f32_e32 v168, v89
	ds_read_b128 v[82:85], v1 offset:26624
	ds_read_b128 v[86:89], v1 offset:26656
	v_cvt_pk_bf16_f32 v71, v159, v69
	v_cvt_pk_bf16_f32 v72, v161, v163
	v_cvt_pk_bf16_f32 v73, v165, v167
	v_pk_add_f32 v[78:79], v[158:159], v[78:79]
	v_exp_f32_e32 v169, v74
	ds_read_b128 v[186:189], v1 offset:26688
	ds_read_b128 v[190:193], v1 offset:26720
	ds_read_b128 v[194:197], v1 offset:31232
	ds_read_b128 v[230:233], v1 offset:31264
	ds_read_b128 v[234:237], v1 offset:31296
	ds_read_b128 v[238:241], v1 offset:31328
	s_waitcnt lgkmcnt(7)
	v_mfma_f32_32x32x16_bf16 v[18:33], v[82:85], v[70:73], v[18:33]
	v_add_f32_e64 v78, v68, v78
	v_add_f32_e64 v79, v69, v79
	v_exp_f32_e32 v173, v75
	v_pk_add_f32 v[78:79], v[160:161], v[78:79]
	v_exp_f32_e32 v175, v76
	v_exp_f32_e32 v177, v77
	v_exp_f32_e32 v183, v80
	v_exp_f32_e32 v185, v81
	v_exp_f32_e32 v172, v90
	v_pk_add_f32 v[78:79], v[162:163], v[78:79]
	v_exp_f32_e32 v174, v91
	v_pk_add_f32 v[78:79], v[164:165], v[78:79]
	v_exp_f32_e32 v176, v92
	v_pk_add_f32 v[78:79], v[166:167], v[78:79]
	v_exp_f32_e32 v178, v93
	v_pk_add_f32 v[78:79], v[168:169], v[78:79]
	v_cvt_pk_bf16_f32 v74, v169, v173
	v_cvt_pk_bf16_f32 v75, v175, v177
	v_cvt_pk_bf16_f32 v76, v179, v181
	v_cvt_pk_bf16_f32 v77, v183, v185
	v_exp_f32_e32 v180, v94
	v_pk_add_f32 v[78:79], v[172:173], v[78:79]
	v_exp_f32_e32 v182, v95
	v_pk_add_f32 v[78:79], v[174:175], v[78:79]
	s_waitcnt lgkmcnt(6)
	v_mfma_f32_32x32x16_bf16 v[18:33], v[86:89], v[74:77], v[18:33]
	v_exp_f32_e32 v184, v96
	v_pk_add_f32 v[78:79], v[176:177], v[78:79]
	v_exp_f32_e32 v170, v97
	v_pk_add_f32 v[78:79], v[178:179], v[78:79]
	v_cvt_pk_bf16_f32 v80, v162, v164
	v_pk_add_f32 v[78:79], v[180:181], v[78:79]
	v_cvt_pk_bf16_f32 v81, v166, v168
	v_pk_add_f32 v[78:79], v[182:183], v[78:79]
	v_cvt_pk_bf16_f32 v67, v176, v178
	v_pk_add_f32 v[78:79], v[184:185], v[78:79]
	v_cvt_pk_bf16_f32 v69, v184, v170
	v_pk_add_f32 v[78:79], v[170:171], v[78:79]
	s_nop 0
	v_add_f32_e32 v171, v78, v79
	v_cvt_pk_bf16_f32 v78, v66, v158
	v_cvt_pk_bf16_f32 v79, v68, v160
	v_cvt_pk_bf16_f32 v66, v172, v174
	v_cvt_pk_bf16_f32 v68, v180, v182
	s_waitcnt lgkmcnt(5)
	v_mfma_f32_32x32x16_bf16 v[18:33], v[186:189], v[78:81], v[18:33]
	s_waitcnt lgkmcnt(4)
	v_mfma_f32_32x32x16_bf16 v[18:33], v[190:193], v[66:69], v[18:33]
	s_waitcnt lgkmcnt(3)
	v_mfma_f32_32x32x16_bf16 v[2:17], v[194:197], v[70:73], v[2:17]
	s_waitcnt lgkmcnt(2)
	v_mfma_f32_32x32x16_bf16 v[2:17], v[230:233], v[74:77], v[2:17]
	s_waitcnt lgkmcnt(1)
	v_mfma_f32_32x32x16_bf16 v[2:17], v[234:237], v[78:81], v[2:17]
	s_waitcnt lgkmcnt(0)
	v_mfma_f32_32x32x16_bf16 v[2:17], v[238:241], v[66:69], v[2:17]
	s_andn2_b64 vcc, exec, s[12:13]
	s_cbranch_vccnz .LBB0_1387
